# accumulator zeroing before each GEMM K-loop: 127 v_mov_b32 -> 64 v_mov_b64 (6 sites)
# speedup vs baseline: 1.0074x; 1.0006x over previous
; template <class Epi, class Sched, bool ALIGN_EPI = false, bool SP2 = false>
; __device__ __forceinline__ void gemm_phase(PG8_LAS unsigned char* lds, const Gemm g, const Sched& S, const Epi& E) {
;     ...
;     f32x4 acc[2][2][4][2];
; #pragma unroll
;     for (int a = 0; a < 2; ++a)
; #pragma unroll
;         for (int b = 0; b < 2; ++b)
; #pragma unroll
;             for (int m = 0; m < 4; ++m)
; #pragma unroll
;                 for (int n = 0; n < 2; ++n) acc[a][b][m][n] = (f32x4){0.f, 0.f, 0.f, 0.f};
;     ...
;         const bool has_next = S.next(ui + 1, nxt);
;         const char* nA = has_next ? (const char*)g.A + (size_t)nxt.pm * tstepA + (size_t)((nxt.pn / g.kdiv) * g.kmul) * 2 : cA; const char* nB = has_next ? (const char*)g.Bt + (size_t)nxt.pn * tstepB : cB;
.LBB0_170:
	s_ashr_i32 s37, s36, 31
	s_lshl_b64 s[46:47], s[36:37], 19
	s_add_u32 s46, s84, s46
	s_addc_u32 s47, s85, s47
	s_and_b64 s[48:49], s[6:7], exec
	s_cselect_b32 s11, s47, s9
	s_cselect_b32 s37, s46, s8
	s_ashr_i32 s35, s34, 31
	s_lshl_b64 s[48:49], s[34:35], 19
	s_add_u32 s48, s92, s48
	s_addc_u32 s49, s93, s49
	s_and_b64 s[52:53], s[6:7], exec
	s_cselect_b32 s35, s49, s51
	s_cselect_b32 s54, s48, s50
	s_add_u32 s8, s8, 0x40080
	s_addc_u32 s9, s9, 0
	s_add_u32 s55, s50, 0x100
	v_mov_b32_e32 v0, 0
	s_addc_u32 s58, s51, 0
	s_mov_b32 s59, -2
	v_mov_b32_e32 v1, v0
	v_mov_b64_e32 v[2:3], 0
	v_mov_b64_e32 v[4:5], 0
	v_mov_b64_e32 v[6:7], 0
	v_mov_b64_e32 v[8:9], 0
	v_mov_b64_e32 v[10:11], 0
	v_mov_b64_e32 v[12:13], 0
	v_mov_b64_e32 v[14:15], 0
	v_mov_b64_e32 v[16:17], 0
	v_mov_b64_e32 v[18:19], 0
	v_mov_b64_e32 v[20:21], 0
	v_mov_b64_e32 v[22:23], 0
	v_mov_b64_e32 v[24:25], 0
	v_mov_b64_e32 v[26:27], 0
	v_mov_b64_e32 v[28:29], 0
	v_mov_b64_e32 v[30:31], 0
	v_mov_b64_e32 v[32:33], 0
	v_mov_b64_e32 v[34:35], 0
	v_mov_b64_e32 v[36:37], 0
	v_mov_b64_e32 v[38:39], 0
	v_mov_b64_e32 v[40:41], 0
	v_mov_b64_e32 v[42:43], 0
	v_mov_b64_e32 v[44:45], 0
	v_mov_b64_e32 v[46:47], 0
	v_mov_b64_e32 v[48:49], 0
	v_mov_b64_e32 v[50:51], 0
	v_mov_b64_e32 v[52:53], 0
	v_mov_b64_e32 v[54:55], 0
	v_mov_b64_e32 v[56:57], 0
	v_mov_b64_e32 v[58:59], 0
	v_mov_b64_e32 v[60:61], 0
	v_mov_b64_e32 v[62:63], 0
	v_mov_b64_e32 v[80:81], 0
	v_mov_b64_e32 v[82:83], 0
	v_mov_b64_e32 v[84:85], 0
	v_mov_b64_e32 v[86:87], 0
	v_mov_b64_e32 v[88:89], 0
	v_mov_b64_e32 v[90:91], 0
	v_mov_b64_e32 v[92:93], 0
	v_mov_b64_e32 v[94:95], 0
	v_mov_b64_e32 v[96:97], 0
	v_mov_b64_e32 v[98:99], 0
	v_mov_b64_e32 v[100:101], 0
	v_mov_b64_e32 v[102:103], 0
	v_mov_b64_e32 v[104:105], 0
	v_mov_b64_e32 v[106:107], 0
	v_mov_b64_e32 v[108:109], 0
	v_mov_b64_e32 v[110:111], 0
	v_mov_b64_e32 v[112:113], 0
	v_mov_b64_e32 v[114:115], 0
	v_mov_b64_e32 v[116:117], 0
	v_mov_b64_e32 v[118:119], 0
	v_mov_b64_e32 v[120:121], 0
	v_mov_b64_e32 v[122:123], 0
	v_mov_b64_e32 v[124:125], 0
	v_mov_b64_e32 v[126:127], 0
	v_mov_b64_e32 v[128:129], 0
	v_mov_b64_e32 v[130:131], 0
	v_mov_b64_e32 v[132:133], 0
	v_mov_b64_e32 v[134:135], 0
	v_mov_b64_e32 v[136:137], 0
	v_mov_b64_e32 v[138:139], 0
	v_mov_b64_e32 v[140:141], 0
	v_mov_b64_e32 v[142:143], 0

; template <class Epi, class Sched, bool ALIGN_EPI = false, bool SP2 = false>
; __device__ __forceinline__ void gemm_phase(PG8_LAS unsigned char* lds, const Gemm g, const Sched& S, const Epi& E) {
;     ...
;         const bool has_next = S.next(ui + 1, nxt);
;         const char* nA = has_next ? (const char*)g.A + (size_t)nxt.pm * tstepA + (size_t)((nxt.pn / g.kdiv) * g.kmul) * 2 : cA; const char* nB = has_next ? (const char*)g.Bt + (size_t)nxt.pn * tstepB : cB;
;     ...
;         for (int a = 0; a < 2; ++a)
; #pragma unroll
;             for (int b = 0; b < 2; ++b)
; #pragma unroll
;                 for (int m = 0; m < 4; ++m)
; #pragma unroll
;                     for (int n = 0; n < 2; ++n) acc[a][b][m][n] = (f32x4){0.f, 0.f, 0.f, 0.f};
;         cur = nxt; cA = nA; cB = nB; ++ui;
.LBB0_711:
	s_ashr_i32 s19, s18, 31
	s_lshl_b64 s[2:3], s[18:19], 19
	s_add_u32 s20, s35, s2
	s_addc_u32 s21, s36, s3
	s_and_b64 s[2:3], s[6:7], exec
	s_cselect_b32 s1, s21, s27
	s_cselect_b32 s2, s20, s26
	s_ashr_i32 s17, s16, 31
	s_lshl_b64 s[22:23], s[16:17], 19
	s_add_u32 s22, s37, s22
	s_addc_u32 s23, s38, s23
	s_and_b64 s[30:31], s[6:7], exec
	s_cselect_b32 s3, s23, s29
	s_cselect_b32 s4, s22, s28
	s_add_u32 s26, s26, 0x40080
	s_addc_u32 s27, s27, 0
	s_add_u32 s9, s28, 0x100
	v_mov_b32_e32 v0, 0
	s_addc_u32 s17, s29, 0
	s_mov_b32 s19, -2
	v_mov_b32_e32 v1, v0
	v_mov_b64_e32 v[2:3], 0
	v_mov_b64_e32 v[4:5], 0
	v_mov_b64_e32 v[6:7], 0
	v_mov_b64_e32 v[8:9], 0
	v_mov_b64_e32 v[10:11], 0
	v_mov_b64_e32 v[12:13], 0
	v_mov_b64_e32 v[14:15], 0
	v_mov_b64_e32 v[16:17], 0
	v_mov_b64_e32 v[18:19], 0
	v_mov_b64_e32 v[20:21], 0
	v_mov_b64_e32 v[22:23], 0
	v_mov_b64_e32 v[24:25], 0
	v_mov_b64_e32 v[26:27], 0
	v_mov_b64_e32 v[28:29], 0
	v_mov_b64_e32 v[30:31], 0
	v_mov_b64_e32 v[32:33], 0
	v_mov_b64_e32 v[34:35], 0
	v_mov_b64_e32 v[36:37], 0
	v_mov_b64_e32 v[38:39], 0
	v_mov_b64_e32 v[40:41], 0
	v_mov_b64_e32 v[42:43], 0
	v_mov_b64_e32 v[44:45], 0
	v_mov_b64_e32 v[46:47], 0
	v_mov_b64_e32 v[48:49], 0
	v_mov_b64_e32 v[50:51], 0
	v_mov_b64_e32 v[52:53], 0
	v_mov_b64_e32 v[54:55], 0
	v_mov_b64_e32 v[56:57], 0
	v_mov_b64_e32 v[58:59], 0
	v_mov_b64_e32 v[60:61], 0
	v_mov_b64_e32 v[62:63], 0
	v_mov_b64_e32 v[64:65], 0
	v_mov_b64_e32 v[66:67], 0
	v_mov_b64_e32 v[68:69], 0
	v_mov_b64_e32 v[70:71], 0
	v_mov_b64_e32 v[72:73], 0
	v_mov_b64_e32 v[74:75], 0
	v_mov_b64_e32 v[76:77], 0
	v_mov_b64_e32 v[78:79], 0
	v_mov_b64_e32 v[80:81], 0
	v_mov_b64_e32 v[82:83], 0
	v_mov_b64_e32 v[84:85], 0
	v_mov_b64_e32 v[86:87], 0
	v_mov_b64_e32 v[88:89], 0
	v_mov_b64_e32 v[90:91], 0
	v_mov_b64_e32 v[92:93], 0
	v_mov_b64_e32 v[94:95], 0
	v_mov_b64_e32 v[96:97], 0
	v_mov_b64_e32 v[98:99], 0
	v_mov_b64_e32 v[100:101], 0
	v_mov_b64_e32 v[102:103], 0
	v_mov_b64_e32 v[104:105], 0
	v_mov_b64_e32 v[106:107], 0
	v_mov_b64_e32 v[108:109], 0
	v_mov_b64_e32 v[110:111], 0
	v_mov_b64_e32 v[112:113], 0
	v_mov_b64_e32 v[114:115], 0
	v_mov_b64_e32 v[116:117], 0
	v_mov_b64_e32 v[118:119], 0
	v_mov_b64_e32 v[120:121], 0
	v_mov_b64_e32 v[122:123], 0
	v_mov_b64_e32 v[124:125], 0
	v_mov_b64_e32 v[126:127], 0

; template <class Epi, class Sched, bool ALIGN_EPI = false, bool SP2 = false>
; __device__ __forceinline__ void gemm_phase(PG8_LAS unsigned char* lds, const Gemm g, const Sched& S, const Epi& E) {
;     ...
;         const bool has_next = S.next(ui + 1, nxt);
;         const char* nA = has_next ? (const char*)g.A + (size_t)nxt.pm * tstepA + (size_t)((nxt.pn / g.kdiv) * g.kmul) * 2 : cA; const char* nB = has_next ? (const char*)g.Bt + (size_t)nxt.pn * tstepB : cB;
;     ...
;         for (int a = 0; a < 2; ++a)
; #pragma unroll
;             for (int b = 0; b < 2; ++b)
; #pragma unroll
;                 for (int m = 0; m < 4; ++m)
; #pragma unroll
;                     for (int n = 0; n < 2; ++n) acc[a][b][m][n] = (f32x4){0.f, 0.f, 0.f, 0.f};
;         cur = nxt; cA = nA; cB = nB; ++ui;
.LBB0_900:
	s_ashr_i32 s25, s24, 31
	s_lshl_b64 s[28:29], s[24:25], 17
	s_add_u32 s28, s33, s28
	s_addc_u32 s29, s48, s29
	s_and_b64 s[8:9], s[8:9], exec
	v_mov_b32_e32 v0, 0
	s_cselect_b32 s25, s29, s31
	s_cselect_b32 s63, s28, s30
	s_mov_b64 s[38:39], 0
	s_mov_b64 s[8:9], -1
	s_mov_b64 s[36:37], 0
	v_mov_b32_e32 v1, v0
	v_mov_b64_e32 v[2:3], 0
	v_mov_b64_e32 v[4:5], 0
	v_mov_b64_e32 v[6:7], 0
	v_mov_b64_e32 v[8:9], 0
	v_mov_b64_e32 v[10:11], 0
	v_mov_b64_e32 v[12:13], 0
	v_mov_b64_e32 v[14:15], 0
	v_mov_b64_e32 v[16:17], 0
	v_mov_b64_e32 v[18:19], 0
	v_mov_b64_e32 v[20:21], 0
	v_mov_b64_e32 v[22:23], 0
	v_mov_b64_e32 v[24:25], 0
	v_mov_b64_e32 v[26:27], 0
	v_mov_b64_e32 v[28:29], 0
	v_mov_b64_e32 v[30:31], 0
	v_mov_b64_e32 v[32:33], 0
	v_mov_b64_e32 v[34:35], 0
	v_mov_b64_e32 v[36:37], 0
	v_mov_b64_e32 v[38:39], 0
	v_mov_b64_e32 v[40:41], 0
	v_mov_b64_e32 v[42:43], 0
	v_mov_b64_e32 v[44:45], 0
	v_mov_b64_e32 v[46:47], 0
	v_mov_b64_e32 v[48:49], 0
	v_mov_b64_e32 v[50:51], 0
	v_mov_b64_e32 v[52:53], 0
	v_mov_b64_e32 v[54:55], 0
	v_mov_b64_e32 v[56:57], 0
	v_mov_b64_e32 v[58:59], 0
	v_mov_b64_e32 v[60:61], 0
	v_mov_b64_e32 v[62:63], 0
	v_mov_b64_e32 v[64:65], 0
	v_mov_b64_e32 v[66:67], 0
	v_mov_b64_e32 v[68:69], 0
	v_mov_b64_e32 v[70:71], 0
	v_mov_b64_e32 v[72:73], 0
	v_mov_b64_e32 v[74:75], 0
	v_mov_b64_e32 v[76:77], 0
	v_mov_b64_e32 v[78:79], 0
	v_mov_b64_e32 v[80:81], 0
	v_mov_b64_e32 v[82:83], 0
	v_mov_b64_e32 v[84:85], 0
	v_mov_b64_e32 v[86:87], 0
	v_mov_b64_e32 v[88:89], 0
	v_mov_b64_e32 v[90:91], 0
	v_mov_b64_e32 v[92:93], 0
	v_mov_b64_e32 v[94:95], 0
	v_mov_b64_e32 v[96:97], 0
	v_mov_b64_e32 v[98:99], 0
	v_mov_b64_e32 v[100:101], 0
	v_mov_b64_e32 v[102:103], 0
	v_mov_b64_e32 v[104:105], 0
	v_mov_b64_e32 v[106:107], 0
	v_mov_b64_e32 v[108:109], 0
	v_mov_b64_e32 v[110:111], 0
	v_mov_b64_e32 v[112:113], 0
	v_mov_b64_e32 v[114:115], 0
	v_mov_b64_e32 v[116:117], 0
	v_mov_b64_e32 v[118:119], 0
	v_mov_b64_e32 v[120:121], 0
	v_mov_b64_e32 v[122:123], 0
	v_mov_b64_e32 v[124:125], 0
	v_mov_b64_e32 v[126:127], 0

; template <class Epi, class Sched, bool ALIGN_EPI = false, bool SP2 = false>
; __device__ __forceinline__ void gemm_phase(PG8_LAS unsigned char* lds, const Gemm g, const Sched& S, const Epi& E) {
;     ...
;         for (int a = 0; a < 2; ++a)
; #pragma unroll
;             for (int b = 0; b < 2; ++b)
; #pragma unroll
;                 for (int m = 0; m < 4; ++m)
; #pragma unroll
;                     for (int n = 0; n < 2; ++n) acc[a][b][m][n] = (f32x4){0.f, 0.f, 0.f, 0.f};
;         cur = nxt; cA = nA; cB = nB; ++ui;
.LBB0_1641:
	s_add_u32 s26, s26, 0x80
	s_addc_u32 s27, s27, 0
	s_add_u32 s72, s28, 0x100
	v_mov_b32_e32 v0, 0
	s_addc_u32 s73, s29, 0
	s_mov_b32 s28, 0
	v_mov_b32_e32 v1, v0
	v_mov_b64_e32 v[2:3], 0
	v_mov_b64_e32 v[4:5], 0
	v_mov_b64_e32 v[6:7], 0
	v_mov_b64_e32 v[8:9], 0
	v_mov_b64_e32 v[10:11], 0
	v_mov_b64_e32 v[12:13], 0
	v_mov_b64_e32 v[14:15], 0
	v_mov_b64_e32 v[16:17], 0
	v_mov_b64_e32 v[18:19], 0
	v_mov_b64_e32 v[20:21], 0
	v_mov_b64_e32 v[22:23], 0
	v_mov_b64_e32 v[24:25], 0
	v_mov_b64_e32 v[26:27], 0
	v_mov_b64_e32 v[28:29], 0
	v_mov_b64_e32 v[30:31], 0
	v_mov_b64_e32 v[32:33], 0
	v_mov_b64_e32 v[34:35], 0
	v_mov_b64_e32 v[36:37], 0
	v_mov_b64_e32 v[38:39], 0
	v_mov_b64_e32 v[40:41], 0
	v_mov_b64_e32 v[42:43], 0
	v_mov_b64_e32 v[44:45], 0
	v_mov_b64_e32 v[46:47], 0
	v_mov_b64_e32 v[48:49], 0
	v_mov_b64_e32 v[50:51], 0
	v_mov_b64_e32 v[52:53], 0
	v_mov_b64_e32 v[54:55], 0
	v_mov_b64_e32 v[56:57], 0
	v_mov_b64_e32 v[58:59], 0
	v_mov_b64_e32 v[60:61], 0
	v_mov_b64_e32 v[62:63], 0
	v_mov_b64_e32 v[64:65], 0
	v_mov_b64_e32 v[66:67], 0
	v_mov_b64_e32 v[68:69], 0
	v_mov_b64_e32 v[70:71], 0
	v_mov_b64_e32 v[72:73], 0
	v_mov_b64_e32 v[74:75], 0
	v_mov_b64_e32 v[76:77], 0
	v_mov_b64_e32 v[78:79], 0
	v_mov_b64_e32 v[80:81], 0
	v_mov_b64_e32 v[82:83], 0
	v_mov_b64_e32 v[84:85], 0
	v_mov_b64_e32 v[86:87], 0
	v_mov_b64_e32 v[88:89], 0
	v_mov_b64_e32 v[90:91], 0
	v_mov_b64_e32 v[92:93], 0
	v_mov_b64_e32 v[94:95], 0
	v_mov_b64_e32 v[96:97], 0
	v_mov_b64_e32 v[98:99], 0
	v_mov_b64_e32 v[100:101], 0
	v_mov_b64_e32 v[102:103], 0
	v_mov_b64_e32 v[104:105], 0
	v_mov_b64_e32 v[106:107], 0
	v_mov_b64_e32 v[108:109], 0
	v_mov_b64_e32 v[110:111], 0
	v_mov_b64_e32 v[112:113], 0
	v_mov_b64_e32 v[114:115], 0
	v_mov_b64_e32 v[116:117], 0
	v_mov_b64_e32 v[118:119], 0
	v_mov_b64_e32 v[120:121], 0
	v_mov_b64_e32 v[122:123], 0
	v_mov_b64_e32 v[124:125], 0
	v_mov_b64_e32 v[126:127], 0

; template <class Epi, class Sched, bool ALIGN_EPI = false, bool SP2 = false>
; __device__ __forceinline__ void gemm_phase(PG8_LAS unsigned char* lds, const Gemm g, const Sched& S, const Epi& E) {
;     ...
;         const bool has_next = S.next(ui + 1, nxt);
;         const char* nA = has_next ? (const char*)g.A + (size_t)nxt.pm * tstepA + (size_t)((nxt.pn / g.kdiv) * g.kmul) * 2 : cA; const char* nB = has_next ? (const char*)g.Bt + (size_t)nxt.pn * tstepB : cB;
;     ...
;         for (int a = 0; a < 2; ++a)
; #pragma unroll
;             for (int b = 0; b < 2; ++b)
; #pragma unroll
;                 for (int m = 0; m < 4; ++m)
; #pragma unroll
;                     for (int n = 0; n < 2; ++n) acc[a][b][m][n] = (f32x4){0.f, 0.f, 0.f, 0.f};
;         cur = nxt; cA = nA; cB = nB; ++ui;
.LBB0_1799:
	s_ashr_i32 s37, s36, 31
	s_lshl_b64 s[8:9], s[36:37], 19
	s_add_u32 s40, s33, s8
	s_addc_u32 s41, s50, s9
	s_and_b64 s[8:9], s[6:7], exec
	s_cselect_b32 s13, s41, s47
	s_cselect_b32 s15, s40, s46
	s_ashr_i32 s35, s34, 31
	s_lshl_b64 s[8:9], s[34:35], 19
	s_add_u32 s42, s51, s8
	s_addc_u32 s43, s52, s9
	s_and_b64 s[8:9], s[6:7], exec
	s_cselect_b32 s35, s43, s45
	s_cselect_b32 s37, s42, s44
	s_add_u32 s8, s46, 0x40080
	s_addc_u32 s9, s47, 0
	s_add_u32 s46, s44, 0x100
	v_mov_b32_e32 v0, 0
	s_addc_u32 s47, s45, 0
	s_mov_b32 s70, -2
	v_mov_b32_e32 v1, v0
	v_mov_b64_e32 v[2:3], 0
	v_mov_b64_e32 v[4:5], 0
	v_mov_b64_e32 v[6:7], 0
	v_mov_b64_e32 v[8:9], 0
	v_mov_b64_e32 v[10:11], 0
	v_mov_b64_e32 v[12:13], 0
	v_mov_b64_e32 v[14:15], 0
	v_mov_b64_e32 v[16:17], 0
	v_mov_b64_e32 v[18:19], 0
	v_mov_b64_e32 v[20:21], 0
	v_mov_b64_e32 v[22:23], 0
	v_mov_b64_e32 v[24:25], 0
	v_mov_b64_e32 v[26:27], 0
	v_mov_b64_e32 v[28:29], 0
	v_mov_b64_e32 v[30:31], 0
	v_mov_b64_e32 v[32:33], 0
	v_mov_b64_e32 v[34:35], 0
	v_mov_b64_e32 v[36:37], 0
	v_mov_b64_e32 v[38:39], 0
	v_mov_b64_e32 v[40:41], 0
	v_mov_b64_e32 v[42:43], 0
	v_mov_b64_e32 v[44:45], 0
	v_mov_b64_e32 v[46:47], 0
	v_mov_b64_e32 v[48:49], 0
	v_mov_b64_e32 v[50:51], 0
	v_mov_b64_e32 v[52:53], 0
	v_mov_b64_e32 v[54:55], 0
	v_mov_b64_e32 v[56:57], 0
	v_mov_b64_e32 v[58:59], 0
	v_mov_b64_e32 v[60:61], 0
	v_mov_b64_e32 v[62:63], 0
	v_mov_b64_e32 v[64:65], 0
	v_mov_b64_e32 v[66:67], 0
	v_mov_b64_e32 v[68:69], 0
	v_mov_b64_e32 v[70:71], 0
	v_mov_b64_e32 v[72:73], 0
	v_mov_b64_e32 v[74:75], 0
	v_mov_b64_e32 v[76:77], 0
	v_mov_b64_e32 v[78:79], 0
	v_mov_b64_e32 v[80:81], 0
	v_mov_b64_e32 v[82:83], 0
	v_mov_b64_e32 v[84:85], 0
	v_mov_b64_e32 v[86:87], 0
	v_mov_b64_e32 v[88:89], 0
	v_mov_b64_e32 v[90:91], 0
	v_mov_b64_e32 v[92:93], 0
	v_mov_b64_e32 v[94:95], 0
	v_mov_b64_e32 v[96:97], 0
	v_mov_b64_e32 v[98:99], 0
	v_mov_b64_e32 v[100:101], 0
	v_mov_b64_e32 v[102:103], 0
	v_mov_b64_e32 v[104:105], 0
	v_mov_b64_e32 v[106:107], 0
	v_mov_b64_e32 v[108:109], 0
	v_mov_b64_e32 v[110:111], 0
	v_mov_b64_e32 v[112:113], 0
	v_mov_b64_e32 v[114:115], 0
	v_mov_b64_e32 v[116:117], 0
	v_mov_b64_e32 v[118:119], 0
	v_mov_b64_e32 v[120:121], 0
	v_mov_b64_e32 v[122:123], 0
	v_mov_b64_e32 v[124:125], 0
	v_mov_b64_e32 v[126:127], 0

; template <class Epi, class Sched, bool ALIGN_EPI = false, bool SP2 = false>
; __device__ __forceinline__ void gemm_phase(PG8_LAS unsigned char* lds, const Gemm g, const Sched& S, const Epi& E) {
;     ...
;         for (int a = 0; a < 2; ++a)
; #pragma unroll
;             for (int b = 0; b < 2; ++b)
; #pragma unroll
;                 for (int m = 0; m < 4; ++m)
; #pragma unroll
;                     for (int n = 0; n < 2; ++n) acc[a][b][m][n] = (f32x4){0.f, 0.f, 0.f, 0.f};
;         cur = nxt; cA = nA; cB = nB; ++ui;
.LBB0_1992:
	s_add_u32 s65, s24, 0x100
	v_mov_b32_e32 v0, 0
	s_addc_u32 s66, s25, 0
	s_mov_b32 s67, -2
	v_mov_b32_e32 v1, v0
	v_mov_b64_e32 v[2:3], 0
	v_mov_b64_e32 v[4:5], 0
	v_mov_b64_e32 v[6:7], 0
	v_mov_b64_e32 v[8:9], 0
	v_mov_b64_e32 v[10:11], 0
	v_mov_b64_e32 v[12:13], 0
	v_mov_b64_e32 v[14:15], 0
	v_mov_b64_e32 v[16:17], 0
	v_mov_b64_e32 v[18:19], 0
	v_mov_b64_e32 v[20:21], 0
	v_mov_b64_e32 v[22:23], 0
	v_mov_b64_e32 v[24:25], 0
	v_mov_b64_e32 v[26:27], 0
	v_mov_b64_e32 v[28:29], 0
	v_mov_b64_e32 v[30:31], 0
	v_mov_b64_e32 v[32:33], 0
	v_mov_b64_e32 v[34:35], 0
	v_mov_b64_e32 v[36:37], 0
	v_mov_b64_e32 v[38:39], 0
	v_mov_b64_e32 v[40:41], 0
	v_mov_b64_e32 v[42:43], 0
	v_mov_b64_e32 v[44:45], 0
	v_mov_b64_e32 v[46:47], 0
	v_mov_b64_e32 v[48:49], 0
	v_mov_b64_e32 v[50:51], 0
	v_mov_b64_e32 v[52:53], 0
	v_mov_b64_e32 v[54:55], 0
	v_mov_b64_e32 v[56:57], 0
	v_mov_b64_e32 v[58:59], 0
	v_mov_b64_e32 v[60:61], 0
	v_mov_b64_e32 v[62:63], 0
	v_mov_b64_e32 v[64:65], 0
	v_mov_b64_e32 v[66:67], 0
	v_mov_b64_e32 v[68:69], 0
	v_mov_b64_e32 v[70:71], 0
	v_mov_b64_e32 v[72:73], 0
	v_mov_b64_e32 v[74:75], 0
	v_mov_b64_e32 v[76:77], 0
	v_mov_b64_e32 v[78:79], 0
	v_mov_b64_e32 v[80:81], 0
	v_mov_b64_e32 v[82:83], 0
	v_mov_b64_e32 v[84:85], 0
	v_mov_b64_e32 v[86:87], 0
	v_mov_b64_e32 v[88:89], 0
	v_mov_b64_e32 v[90:91], 0
	v_mov_b64_e32 v[92:93], 0
	v_mov_b64_e32 v[94:95], 0
	v_mov_b64_e32 v[96:97], 0
	v_mov_b64_e32 v[98:99], 0
	v_mov_b64_e32 v[100:101], 0
	v_mov_b64_e32 v[102:103], 0
	v_mov_b64_e32 v[104:105], 0
	v_mov_b64_e32 v[106:107], 0
	v_mov_b64_e32 v[108:109], 0
	v_mov_b64_e32 v[110:111], 0
	v_mov_b64_e32 v[112:113], 0
	v_mov_b64_e32 v[114:115], 0
	v_mov_b64_e32 v[116:117], 0
	v_mov_b64_e32 v[118:119], 0
	v_mov_b64_e32 v[120:121], 0
	v_mov_b64_e32 v[122:123], 0
	v_mov_b64_e32 v[124:125], 0
	v_mov_b64_e32 v[126:127], 0
